# P3 pooling pre-phase: the up-to-16 window-row loads of an item are issued together under their lane masks, one wait, then accumulated in the original order (was one wait per load)
# speedup vs baseline: 1.0269x; 1.0250x over previous
; __global__ void __launch_bounds__(512, 2) hybrid_fwd(Args args) {
;     ...
;             for (int it = tid; it < 256 * 32; it += 512) {
;                 const int t = pu.pm * 256 + (it >> 5), cg8 = pu.pn * 32 + (it & 31), tl = t & 8191, w = 2 << (cg8 >> 4);
;                 const bf16_t* xp = XP + (size_t)t * 512 + cg8 * 8;
;                 float sum[8];
; #pragma unroll
;                 for (int e = 0; e < 8; ++e) sum[e] = 0.f;
;                 u32x4 x0 = (u32x4){0u, 0u, 0u, 0u};
; #pragma unroll
;                 for (int j = 0; j < 16; ++j) {
;                     if (j < w && tl - j >= 0) {
;                         const u32x4 v = *(const u32x4*)(xp - (size_t)j * 512);
;                         if (j == 0) x0 = v;
; #pragma unroll
;                         for (int e = 0; e < 4; ++e) { sum[2 * e] += __builtin_bit_cast(float, v[e] << 16); sum[2 * e + 1] += __builtin_bit_cast(float, v[e] & 0xffff0000u); }
;                     }
;                 }
.LBB0_371:
	v_ashrrev_i32_e32 v0, 5, v29
	v_add_u32_e32 v16, s66, v0
	v_ashrrev_i32_e32 v17, 31, v16
	v_lshlrev_b64 v[0:1], 10, v[16:17]
	v_mov_b32_e32 v24, 0
	v_lshl_add_u64 v[22:23], v[8:9], 0, v[0:1]
	v_mov_b32_e32 v0, 0
	v_mov_b32_e32 v25, 0
	v_mov_b32_e32 v18, 0
	v_mov_b32_e32 v19, 0
	v_mov_b32_e32 v14, 0
	v_mov_b32_e32 v15, v24
	v_mov_b32_e32 v12, v24
	v_mov_b32_e32 v13, v24
	v_mov_b32_e32 v20, 0
	v_mov_b32_e32 v21, 0
	v_mov_b32_e32 v1, 0
	v_mov_b32_e32 v2, 0
	v_mov_b32_e32 v3, 0
	v_and_b32_e32 v30, 0x1fff, v16
	v_add_co_u32_e32 v104, vcc, 0xfffff000, v22
	s_nop 1
	v_addc_co_u32_e32 v105, vcc, -1, v23, vcc
	v_add_co_u32_e32 v106, vcc, 0xffffe000, v22
	s_nop 1
	v_addc_co_u32_e32 v107, vcc, -1, v23, vcc
	v_add_co_u32_e32 v108, vcc, 0xffffd000, v22
	s_nop 1
	v_addc_co_u32_e32 v109, vcc, -1, v23, vcc
	s_and_saveexec_b64 s[58:59], s[8:9]
	global_load_dwordx4 v[0:3], v[22:23], off
	s_or_b64 exec, exec, s[58:59]
	v_cmp_ne_u32_e32 vcc, 0, v30
	s_and_b64 s[70:71], s[56:57], vcc
	s_and_saveexec_b64 s[58:59], s[70:71]
	global_load_dwordx4 v[44:47], v[22:23], off offset:-1024
	s_or_b64 exec, exec, s[58:59]
	v_cmp_lt_u32_e32 vcc, 1, v30
	s_and_b64 s[70:71], s[10:11], vcc
	s_and_saveexec_b64 s[58:59], s[70:71]
	global_load_dwordx4 v[48:51], v[22:23], off offset:-2048
	s_or_b64 exec, exec, s[58:59]
	v_cmp_lt_u32_e32 vcc, 2, v30
	s_and_b64 s[70:71], s[12:13], vcc
	s_and_saveexec_b64 s[58:59], s[70:71]
	global_load_dwordx4 v[52:55], v[22:23], off offset:-3072
	s_or_b64 exec, exec, s[58:59]
	v_cmp_lt_u32_e32 vcc, 3, v30
	s_and_b64 s[70:71], s[14:15], vcc
	s_and_saveexec_b64 s[58:59], s[70:71]
	global_load_dwordx4 v[56:59], v[104:105], off
	s_or_b64 exec, exec, s[58:59]
	v_cmp_lt_u32_e32 vcc, 4, v30
	s_and_b64 s[70:71], s[16:17], vcc
	s_and_saveexec_b64 s[58:59], s[70:71]
	global_load_dwordx4 v[60:63], v[104:105], off offset:-1024
	s_or_b64 exec, exec, s[58:59]
	v_cmp_lt_u32_e32 vcc, 5, v30
	s_and_b64 s[70:71], s[18:19], vcc
	s_and_saveexec_b64 s[58:59], s[70:71]
	global_load_dwordx4 v[64:67], v[104:105], off offset:-2048
	s_or_b64 exec, exec, s[58:59]
	v_cmp_lt_u32_e32 vcc, 6, v30
	s_and_b64 s[70:71], s[20:21], vcc
	s_and_saveexec_b64 s[58:59], s[70:71]
	global_load_dwordx4 v[68:71], v[104:105], off offset:-3072
	s_or_b64 exec, exec, s[58:59]
	v_cmp_lt_u32_e32 vcc, 7, v30
	s_and_b64 s[70:71], s[22:23], vcc
	s_and_saveexec_b64 s[58:59], s[70:71]
	global_load_dwordx4 v[72:75], v[106:107], off
	s_or_b64 exec, exec, s[58:59]
	v_cmp_lt_u32_e32 vcc, 8, v30
	s_and_b64 s[70:71], s[24:25], vcc
	s_and_saveexec_b64 s[58:59], s[70:71]
	global_load_dwordx4 v[76:79], v[106:107], off offset:-1024
	s_or_b64 exec, exec, s[58:59]
	v_cmp_lt_u32_e32 vcc, 9, v30
	s_and_b64 s[70:71], s[26:27], vcc
	s_and_saveexec_b64 s[58:59], s[70:71]
	global_load_dwordx4 v[80:83], v[106:107], off offset:-2048
	s_or_b64 exec, exec, s[58:59]
	v_cmp_lt_u32_e32 vcc, 10, v30
	s_and_b64 s[70:71], s[28:29], vcc
	s_and_saveexec_b64 s[58:59], s[70:71]
	global_load_dwordx4 v[84:87], v[106:107], off offset:-3072
	s_or_b64 exec, exec, s[58:59]
	v_cmp_lt_u32_e32 vcc, 11, v30
	s_and_b64 s[70:71], s[30:31], vcc
	s_and_saveexec_b64 s[58:59], s[70:71]
	global_load_dwordx4 v[88:91], v[108:109], off
	s_or_b64 exec, exec, s[58:59]
	v_cmp_lt_u32_e32 vcc, 12, v30
	s_and_b64 s[70:71], s[34:35], vcc
	s_and_saveexec_b64 s[58:59], s[70:71]
	global_load_dwordx4 v[92:95], v[108:109], off offset:-1024
	s_or_b64 exec, exec, s[58:59]
	v_cmp_lt_u32_e32 vcc, 13, v30
	s_and_b64 s[70:71], s[36:37], vcc
	s_and_saveexec_b64 s[58:59], s[70:71]
	global_load_dwordx4 v[96:99], v[108:109], off offset:-2048
	s_or_b64 exec, exec, s[58:59]
	v_cmp_lt_u32_e32 vcc, 14, v30
	s_and_b64 s[70:71], s[38:39], vcc
	s_and_saveexec_b64 s[58:59], s[70:71]
	global_load_dwordx4 v[100:103], v[108:109], off offset:-3072
	s_or_b64 exec, exec, s[58:59]
	s_waitcnt vmcnt(0)
	s_and_saveexec_b64 s[58:59], s[8:9]
	v_lshlrev_b32_e32 v24, 16, v3
	v_and_b32_e32 v25, 0xffff0000, v3
	v_lshlrev_b32_e32 v12, 16, v0
	v_and_b32_e32 v13, 0xffff0000, v0
	v_lshlrev_b32_e32 v14, 16, v1
	v_and_b32_e32 v15, 0xffff0000, v1
	v_lshlrev_b32_e32 v20, 16, v2
	v_and_b32_e32 v21, 0xffff0000, v2
	v_pk_add_f32 v[24:25], v[24:25], 0 op_sel_hi:[1,0]
	v_pk_add_f32 v[18:19], v[12:13], 0 op_sel_hi:[1,0]
	v_pk_add_f32 v[14:15], v[14:15], 0 op_sel_hi:[1,0]
	v_pk_add_f32 v[12:13], v[20:21], 0 op_sel_hi:[1,0]
	v_mov_b32_e32 v20, v24
	v_mov_b32_e32 v21, v25
	s_or_b64 exec, exec, s[58:59]
	v_cmp_ne_u32_e32 vcc, 0, v30
	s_and_b64 s[70:71], s[56:57], vcc
	s_and_saveexec_b64 s[58:59], s[70:71]
	v_lshlrev_b32_e32 v32, 16, v44
	v_and_b32_e32 v33, 0xffff0000, v44
	v_lshlrev_b32_e32 v34, 16, v45
	v_and_b32_e32 v35, 0xffff0000, v45
	v_lshlrev_b32_e32 v36, 16, v46
	v_and_b32_e32 v37, 0xffff0000, v46
	v_lshlrev_b32_e32 v38, 16, v47
	v_and_b32_e32 v39, 0xffff0000, v47
	v_pk_add_f32 v[18:19], v[18:19], v[32:33]
	v_pk_add_f32 v[14:15], v[14:15], v[34:35]
	v_pk_add_f32 v[12:13], v[12:13], v[36:37]
	v_pk_add_f32 v[20:21], v[20:21], v[38:39]
	s_or_b64 exec, exec, s[58:59]
	v_cmp_lt_u32_e32 vcc, 1, v30
	s_and_b64 s[70:71], s[10:11], vcc
	s_and_saveexec_b64 s[58:59], s[70:71]
	v_lshlrev_b32_e32 v32, 16, v48
	v_and_b32_e32 v33, 0xffff0000, v48
	v_lshlrev_b32_e32 v34, 16, v49
	v_and_b32_e32 v35, 0xffff0000, v49
	v_lshlrev_b32_e32 v36, 16, v50
	v_and_b32_e32 v37, 0xffff0000, v50
	v_lshlrev_b32_e32 v38, 16, v51
	v_and_b32_e32 v39, 0xffff0000, v51
	v_pk_add_f32 v[18:19], v[18:19], v[32:33]
	v_pk_add_f32 v[14:15], v[14:15], v[34:35]
	v_pk_add_f32 v[12:13], v[12:13], v[36:37]
	v_pk_add_f32 v[20:21], v[20:21], v[38:39]
	s_or_b64 exec, exec, s[58:59]
	v_cmp_lt_u32_e32 vcc, 2, v30
	s_and_b64 s[70:71], s[12:13], vcc
; __global__ void __launch_bounds__(512, 2) hybrid_fwd(Args args) {
;     ...
;                 for (int j = 0; j < 16; ++j) {
;                     if (j < w && tl - j >= 0) {
;                         const u32x4 v = *(const u32x4*)(xp - (size_t)j * 512);
;                         if (j == 0) x0 = v;
; #pragma unroll
;                         for (int e = 0; e < 4; ++e) { sum[2 * e] += __builtin_bit_cast(float, v[e] << 16); sum[2 * e + 1] += __builtin_bit_cast(float, v[e] & 0xffff0000u); }
;                     }
;                 }
	s_and_saveexec_b64 s[58:59], s[70:71]
	v_lshlrev_b32_e32 v32, 16, v52
	v_and_b32_e32 v33, 0xffff0000, v52
	v_lshlrev_b32_e32 v34, 16, v53
	v_and_b32_e32 v35, 0xffff0000, v53
	v_lshlrev_b32_e32 v36, 16, v54
	v_and_b32_e32 v37, 0xffff0000, v54
	v_lshlrev_b32_e32 v38, 16, v55
	v_and_b32_e32 v39, 0xffff0000, v55
	v_pk_add_f32 v[18:19], v[18:19], v[32:33]
	v_pk_add_f32 v[14:15], v[14:15], v[34:35]
	v_pk_add_f32 v[12:13], v[12:13], v[36:37]
	v_pk_add_f32 v[20:21], v[20:21], v[38:39]
	s_or_b64 exec, exec, s[58:59]
	v_cmp_lt_u32_e32 vcc, 3, v30
	s_and_b64 s[70:71], s[14:15], vcc
	s_and_saveexec_b64 s[58:59], s[70:71]
	v_lshlrev_b32_e32 v32, 16, v56
	v_and_b32_e32 v33, 0xffff0000, v56
	v_lshlrev_b32_e32 v34, 16, v57
	v_and_b32_e32 v35, 0xffff0000, v57
	v_lshlrev_b32_e32 v36, 16, v58
	v_and_b32_e32 v37, 0xffff0000, v58
	v_lshlrev_b32_e32 v38, 16, v59
	v_and_b32_e32 v39, 0xffff0000, v59
	v_pk_add_f32 v[18:19], v[18:19], v[32:33]
	v_pk_add_f32 v[14:15], v[14:15], v[34:35]
	v_pk_add_f32 v[12:13], v[12:13], v[36:37]
	v_pk_add_f32 v[20:21], v[20:21], v[38:39]
	s_or_b64 exec, exec, s[58:59]
	v_cmp_lt_u32_e32 vcc, 4, v30
	s_and_b64 s[70:71], s[16:17], vcc
	s_and_saveexec_b64 s[58:59], s[70:71]
	v_lshlrev_b32_e32 v32, 16, v60
	v_and_b32_e32 v33, 0xffff0000, v60
	v_lshlrev_b32_e32 v34, 16, v61
	v_and_b32_e32 v35, 0xffff0000, v61
	v_lshlrev_b32_e32 v36, 16, v62
	v_and_b32_e32 v37, 0xffff0000, v62
	v_lshlrev_b32_e32 v38, 16, v63
	v_and_b32_e32 v39, 0xffff0000, v63
	v_pk_add_f32 v[18:19], v[18:19], v[32:33]
	v_pk_add_f32 v[14:15], v[14:15], v[34:35]
	v_pk_add_f32 v[12:13], v[12:13], v[36:37]
	v_pk_add_f32 v[20:21], v[20:21], v[38:39]
	s_or_b64 exec, exec, s[58:59]
	v_cmp_lt_u32_e32 vcc, 5, v30
	s_and_b64 s[70:71], s[18:19], vcc
	s_and_saveexec_b64 s[58:59], s[70:71]
	v_lshlrev_b32_e32 v32, 16, v64
	v_and_b32_e32 v33, 0xffff0000, v64
	v_lshlrev_b32_e32 v34, 16, v65
	v_and_b32_e32 v35, 0xffff0000, v65
	v_lshlrev_b32_e32 v36, 16, v66
	v_and_b32_e32 v37, 0xffff0000, v66
	v_lshlrev_b32_e32 v38, 16, v67
	v_and_b32_e32 v39, 0xffff0000, v67
	v_pk_add_f32 v[18:19], v[18:19], v[32:33]
	v_pk_add_f32 v[14:15], v[14:15], v[34:35]
	v_pk_add_f32 v[12:13], v[12:13], v[36:37]
	v_pk_add_f32 v[20:21], v[20:21], v[38:39]
	s_or_b64 exec, exec, s[58:59]
	v_cmp_lt_u32_e32 vcc, 6, v30
	s_and_b64 s[70:71], s[20:21], vcc
	s_and_saveexec_b64 s[58:59], s[70:71]
	v_lshlrev_b32_e32 v32, 16, v68
	v_and_b32_e32 v33, 0xffff0000, v68
	v_lshlrev_b32_e32 v34, 16, v69
	v_and_b32_e32 v35, 0xffff0000, v69
	v_lshlrev_b32_e32 v36, 16, v70
	v_and_b32_e32 v37, 0xffff0000, v70
	v_lshlrev_b32_e32 v38, 16, v71
	v_and_b32_e32 v39, 0xffff0000, v71
	v_pk_add_f32 v[18:19], v[18:19], v[32:33]
	v_pk_add_f32 v[14:15], v[14:15], v[34:35]
	v_pk_add_f32 v[12:13], v[12:13], v[36:37]
	v_pk_add_f32 v[20:21], v[20:21], v[38:39]
	s_or_b64 exec, exec, s[58:59]
	v_cmp_lt_u32_e32 vcc, 7, v30
	s_and_b64 s[70:71], s[22:23], vcc
	s_and_saveexec_b64 s[58:59], s[70:71]
	v_lshlrev_b32_e32 v32, 16, v72
	v_and_b32_e32 v33, 0xffff0000, v72
	v_lshlrev_b32_e32 v34, 16, v73
	v_and_b32_e32 v35, 0xffff0000, v73
	v_lshlrev_b32_e32 v36, 16, v74
	v_and_b32_e32 v37, 0xffff0000, v74
	v_lshlrev_b32_e32 v38, 16, v75
	v_and_b32_e32 v39, 0xffff0000, v75
	v_pk_add_f32 v[18:19], v[18:19], v[32:33]
	v_pk_add_f32 v[14:15], v[14:15], v[34:35]
	v_pk_add_f32 v[12:13], v[12:13], v[36:37]
	v_pk_add_f32 v[20:21], v[20:21], v[38:39]
	s_or_b64 exec, exec, s[58:59]
	v_cmp_lt_u32_e32 vcc, 8, v30
	s_and_b64 s[70:71], s[24:25], vcc
	s_and_saveexec_b64 s[58:59], s[70:71]
	v_lshlrev_b32_e32 v32, 16, v76
	v_and_b32_e32 v33, 0xffff0000, v76
	v_lshlrev_b32_e32 v34, 16, v77
	v_and_b32_e32 v35, 0xffff0000, v77
	v_lshlrev_b32_e32 v36, 16, v78
	v_and_b32_e32 v37, 0xffff0000, v78
	v_lshlrev_b32_e32 v38, 16, v79
; __global__ void __launch_bounds__(512, 2) hybrid_fwd(Args args) {
;     ...
;                 for (int j = 0; j < 16; ++j) {
;                     if (j < w && tl - j >= 0) {
;                         const u32x4 v = *(const u32x4*)(xp - (size_t)j * 512);
;                         if (j == 0) x0 = v;
; #pragma unroll
;                         for (int e = 0; e < 4; ++e) { sum[2 * e] += __builtin_bit_cast(float, v[e] << 16); sum[2 * e + 1] += __builtin_bit_cast(float, v[e] & 0xffff0000u); }
;                     }
;                 }
	v_and_b32_e32 v39, 0xffff0000, v79
	v_pk_add_f32 v[18:19], v[18:19], v[32:33]
	v_pk_add_f32 v[14:15], v[14:15], v[34:35]
	v_pk_add_f32 v[12:13], v[12:13], v[36:37]
	v_pk_add_f32 v[20:21], v[20:21], v[38:39]
	s_or_b64 exec, exec, s[58:59]
	v_cmp_lt_u32_e32 vcc, 9, v30
	s_and_b64 s[70:71], s[26:27], vcc
	s_and_saveexec_b64 s[58:59], s[70:71]
	v_lshlrev_b32_e32 v32, 16, v80
	v_and_b32_e32 v33, 0xffff0000, v80
	v_lshlrev_b32_e32 v34, 16, v81
	v_and_b32_e32 v35, 0xffff0000, v81
	v_lshlrev_b32_e32 v36, 16, v82
	v_and_b32_e32 v37, 0xffff0000, v82
	v_lshlrev_b32_e32 v38, 16, v83
	v_and_b32_e32 v39, 0xffff0000, v83
	v_pk_add_f32 v[18:19], v[18:19], v[32:33]
	v_pk_add_f32 v[14:15], v[14:15], v[34:35]
	v_pk_add_f32 v[12:13], v[12:13], v[36:37]
	v_pk_add_f32 v[20:21], v[20:21], v[38:39]
	s_or_b64 exec, exec, s[58:59]
	v_cmp_lt_u32_e32 vcc, 10, v30
	s_and_b64 s[70:71], s[28:29], vcc
	s_and_saveexec_b64 s[58:59], s[70:71]
	v_lshlrev_b32_e32 v32, 16, v84
	v_and_b32_e32 v33, 0xffff0000, v84
	v_lshlrev_b32_e32 v34, 16, v85
	v_and_b32_e32 v35, 0xffff0000, v85
	v_lshlrev_b32_e32 v36, 16, v86
	v_and_b32_e32 v37, 0xffff0000, v86
	v_lshlrev_b32_e32 v38, 16, v87
	v_and_b32_e32 v39, 0xffff0000, v87
	v_pk_add_f32 v[18:19], v[18:19], v[32:33]
	v_pk_add_f32 v[14:15], v[14:15], v[34:35]
	v_pk_add_f32 v[12:13], v[12:13], v[36:37]
	v_pk_add_f32 v[20:21], v[20:21], v[38:39]
	s_or_b64 exec, exec, s[58:59]
	v_cmp_lt_u32_e32 vcc, 11, v30
	s_and_b64 s[70:71], s[30:31], vcc
	s_and_saveexec_b64 s[58:59], s[70:71]
	v_lshlrev_b32_e32 v32, 16, v88
	v_and_b32_e32 v33, 0xffff0000, v88
	v_lshlrev_b32_e32 v34, 16, v89
	v_and_b32_e32 v35, 0xffff0000, v89
	v_lshlrev_b32_e32 v36, 16, v90
	v_and_b32_e32 v37, 0xffff0000, v90
	v_lshlrev_b32_e32 v38, 16, v91
	v_and_b32_e32 v39, 0xffff0000, v91
	v_pk_add_f32 v[18:19], v[18:19], v[32:33]
	v_pk_add_f32 v[14:15], v[14:15], v[34:35]
	v_pk_add_f32 v[12:13], v[12:13], v[36:37]
	v_pk_add_f32 v[20:21], v[20:21], v[38:39]
	s_or_b64 exec, exec, s[58:59]
	v_cmp_lt_u32_e32 vcc, 12, v30
	s_and_b64 s[70:71], s[34:35], vcc
	s_and_saveexec_b64 s[58:59], s[70:71]
	v_lshlrev_b32_e32 v32, 16, v92
	v_and_b32_e32 v33, 0xffff0000, v92
	v_lshlrev_b32_e32 v34, 16, v93
	v_and_b32_e32 v35, 0xffff0000, v93
	v_lshlrev_b32_e32 v36, 16, v94
	v_and_b32_e32 v37, 0xffff0000, v94
	v_lshlrev_b32_e32 v38, 16, v95
	v_and_b32_e32 v39, 0xffff0000, v95
	v_pk_add_f32 v[18:19], v[18:19], v[32:33]
	v_pk_add_f32 v[14:15], v[14:15], v[34:35]
	v_pk_add_f32 v[12:13], v[12:13], v[36:37]
	v_pk_add_f32 v[20:21], v[20:21], v[38:39]
	s_or_b64 exec, exec, s[58:59]
	v_cmp_lt_u32_e32 vcc, 13, v30
	s_and_b64 s[70:71], s[36:37], vcc
	s_and_saveexec_b64 s[58:59], s[70:71]
	v_lshlrev_b32_e32 v32, 16, v96
	v_and_b32_e32 v33, 0xffff0000, v96
	v_lshlrev_b32_e32 v34, 16, v97
	v_and_b32_e32 v35, 0xffff0000, v97
	v_lshlrev_b32_e32 v36, 16, v98
	v_and_b32_e32 v37, 0xffff0000, v98
	v_lshlrev_b32_e32 v38, 16, v99
	v_and_b32_e32 v39, 0xffff0000, v99
	v_pk_add_f32 v[18:19], v[18:19], v[32:33]
	v_pk_add_f32 v[14:15], v[14:15], v[34:35]
	v_pk_add_f32 v[12:13], v[12:13], v[36:37]
	v_pk_add_f32 v[20:21], v[20:21], v[38:39]
	s_or_b64 exec, exec, s[58:59]
	v_cmp_lt_u32_e32 vcc, 14, v30
	s_and_b64 s[70:71], s[38:39], vcc
	s_and_saveexec_b64 s[58:59], s[70:71]
	v_lshlrev_b32_e32 v32, 16, v100
	v_and_b32_e32 v33, 0xffff0000, v100
	v_lshlrev_b32_e32 v34, 16, v101
	v_and_b32_e32 v35, 0xffff0000, v101
	v_lshlrev_b32_e32 v36, 16, v102
	v_and_b32_e32 v37, 0xffff0000, v102
	v_lshlrev_b32_e32 v38, 16, v103
	v_and_b32_e32 v39, 0xffff0000, v103
	v_pk_add_f32 v[18:19], v[18:19], v[32:33]
	v_pk_add_f32 v[14:15], v[14:15], v[34:35]
	v_pk_add_f32 v[12:13], v[12:13], v[36:37]
	v_pk_add_f32 v[20:21], v[20:21], v[38:39]
	s_or_b64 exec, exec, s[58:59]
	s_branch .LBB0_370
